# P0 x->bf16 conversion: four items per pass, eight loads in flight per lane
# speedup vs baseline: 1.0080x; 1.0080x over previous
; DI unsigned pack2bf(float a, float b) { const f2_t v = {a, b}; return __builtin_bit_cast(unsigned, __builtin_convertvector(v, bf2_t)); }
; DI void cvt_bf16(const float* __restrict__ src, long n, u16* __restrict__ dst, int vb, int nvb) {
;   for (long idx = (long)vb * 256 + VT; idx < n / 8; idx += (long)nvb * 256) {
;     float4 a = reinterpret_cast<const float4*>(src)[idx * 2], b = reinterpret_cast<const float4*>(src)[idx * 2 + 1];
;     reinterpret_cast<uint4*>(dst)[idx] = make_uint4(pack2bf(a.x, a.y), pack2bf(a.z, a.w), pack2bf(b.x, b.y), pack2bf(b.z, b.w));
;   }
; }
.LBB0_17:
	s_load_dwordx2 s[4:5], s[0:1], 0xb0
	v_lshrrev_b32_e32 v190, 8, v189
	s_lshl_b32 s3, s74, 1
	v_add_u32_e32 v130, s3, v190
	v_ashrrev_i32_e32 v131, 31, v130
	s_waitcnt lgkmcnt(0)
	s_lshl_b32 s14, s4, 1
	v_lshlrev_b64 v[128:129], 8, v[130:131]
	v_and_b32_e32 v191, 0xff, v189
	v_or_b32_e32 v128, v128, v191
	s_mov_b64 s[4:5], 0x400000
	s_ashr_i32 s15, s14, 31
	v_cmp_gt_i64_e32 vcc, s[4:5], v[128:129]
	s_lshl_b64 s[12:13], s[14:15], 8
	s_and_saveexec_b64 s[4:5], vcc
	s_cbranch_execz .LBB0_20
	v_lshlrev_b64 v[0:1], 12, v[130:131]
	v_lshlrev_b64 v[2:3], 13, v[130:131]
	v_lshl_or_b32 v0, v191, 4, v0
	v_lshl_or_b32 v2, v191, 5, v2
	v_lshl_add_u64 v[0:1], s[78:79], 0, v[0:1]
	s_mov_b64 s[6:7], 0x4000000
	v_lshl_add_u64 v[2:3], s[52:53], 0, v[2:3]
	v_lshl_add_u64 v[0:1], v[0:1], 0, s[6:7]
	s_lshl_b64 s[6:7], s[14:15], 12
	v_lshl_add_u64 v[2:3], v[2:3], 0, 16
	s_lshl_b64 s[8:9], s[14:15], 13
	s_mov_b64 s[10:11], 0
	s_mov_b64 s[16:17], 0x3fffff
	v_mov_b64_e32 v[4:5], v[128:129]
	s_mov_b32 s18, 8
.Lp0_cvt_loop:
	global_load_dwordx4 v[144:147], v[2:3], off offset:-16
	global_load_dwordx4 v[148:151], v[2:3], off
	v_lshl_add_u64 v[2:3], v[2:3], 0, s[8:9]
	global_load_dwordx4 v[152:155], v[2:3], off offset:-16
	global_load_dwordx4 v[156:159], v[2:3], off
	v_lshl_add_u64 v[2:3], v[2:3], 0, s[8:9]
	global_load_dwordx4 v[160:163], v[2:3], off offset:-16
	global_load_dwordx4 v[164:167], v[2:3], off
	v_lshl_add_u64 v[2:3], v[2:3], 0, s[8:9]
	global_load_dwordx4 v[168:171], v[2:3], off offset:-16
	global_load_dwordx4 v[172:175], v[2:3], off
	v_lshl_add_u64 v[2:3], v[2:3], 0, s[8:9]
	s_waitcnt vmcnt(6)
	v_cvt_pk_bf16_f32 v144, v144, v145
	v_cvt_pk_bf16_f32 v145, v146, v147
	v_cvt_pk_bf16_f32 v146, v148, v149
	v_cvt_pk_bf16_f32 v147, v150, v151
	global_store_dwordx4 v[0:1], v[144:147], off
	v_lshl_add_u64 v[0:1], v[0:1], 0, s[6:7]
	s_waitcnt vmcnt(5)
	v_cvt_pk_bf16_f32 v152, v152, v153
	v_cvt_pk_bf16_f32 v153, v154, v155
	v_cvt_pk_bf16_f32 v154, v156, v157
	v_cvt_pk_bf16_f32 v155, v158, v159
	global_store_dwordx4 v[0:1], v[152:155], off
	v_lshl_add_u64 v[0:1], v[0:1], 0, s[6:7]
	s_waitcnt vmcnt(4)
	v_cvt_pk_bf16_f32 v160, v160, v161
	v_cvt_pk_bf16_f32 v161, v162, v163
	v_cvt_pk_bf16_f32 v162, v164, v165
	v_cvt_pk_bf16_f32 v163, v166, v167
	global_store_dwordx4 v[0:1], v[160:163], off
	v_lshl_add_u64 v[0:1], v[0:1], 0, s[6:7]
	s_waitcnt vmcnt(3)
	v_cvt_pk_bf16_f32 v168, v168, v169
	v_cvt_pk_bf16_f32 v169, v170, v171
	v_cvt_pk_bf16_f32 v170, v172, v173
	v_cvt_pk_bf16_f32 v171, v174, v175
	global_store_dwordx4 v[0:1], v[168:171], off
	v_lshl_add_u64 v[0:1], v[0:1], 0, s[6:7]
	s_sub_i32 s18, s18, 1
	s_cmp_lg_u32 s18, 0
	s_cbranch_scc1 .Lp0_cvt_loop
